# P4 y_ret first batch requested at the last trip's segment D (one segment of lead) on top of P5/P6 prefetch
# speedup vs baseline: 1.0036x; 1.0036x over previous
.LBB0_689:
	ds_read_b128 v[146:149], v160
	ds_read_b128 v[150:153], v160 offset:1024
	ds_read_b128 v[154:157], v160 offset:2048
	ds_read_b128 v[164:167], v160 offset:3072
	ds_read_b128 v[168:171], v161
	ds_read_b128 v[172:175], v161 offset:1024
	ds_read_b128 v[176:179], v161 offset:2048
	ds_read_b128 v[180:183], v161 offset:3072
	s_add_u32 s48, s81, s10
	s_addc_u32 s49, s82, 0
	s_add_u32 s85, s83, s10
	s_addc_u32 s86, s84, 0
	s_cmp_eq_u32 s10, s0
	s_cselect_b32 s51, s5, s49
	s_cselect_b32 s50, s43, s48
	s_cselect_b32 s49, s41, s86
	s_cselect_b32 s48, s79, s85
	s_add_i32 s86, s56, 0xc000
	v_lshl_add_u64 v[216:217], v[130:131], 0, s[10:11]
	s_mov_b32 m0, s86
	s_add_i32 s85, s56, 0xe000
	ds_read_b128 v[184:187], v162
	ds_read_b128 v[188:191], v162 offset:1024
	ds_read_b128 v[192:195], v162 offset:2048
	ds_read_b128 v[196:199], v162 offset:3072
	ds_read_b128 v[200:203], v162 offset:4096
	ds_read_b128 v[204:207], v162 offset:5120
	ds_read_b128 v[208:211], v162 offset:6144
	ds_read_b128 v[212:215], v162 offset:7168
	global_load_lds_dwordx4 v[216:217], off
	v_lshl_add_u64 v[216:217], v[132:133], 0, s[10:11]
	s_mov_b32 m0, s85
	s_nop 0
	global_load_lds_dwordx4 v[216:217], off
	s_waitcnt vmcnt(8)
	s_waitcnt lgkmcnt(0)
	s_barrier
	s_setprio 1
	s_waitcnt lgkmcnt(0)
	v_mfma_f32_16x16x32_bf16 v[126:129], v[146:149], v[184:187], v[126:129]
	v_mfma_f32_16x16x32_bf16 v[122:125], v[154:157], v[184:187], v[122:125]
	v_mfma_f32_16x16x32_bf16 v[110:113], v[146:149], v[192:195], v[110:113]
	v_mfma_f32_16x16x32_bf16 v[106:109], v[154:157], v[192:195], v[106:109]
	v_mfma_f32_16x16x32_bf16 v[94:97], v[146:149], v[200:203], v[94:97]
	v_mfma_f32_16x16x32_bf16 v[90:93], v[154:157], v[200:203], v[90:93]
	v_mfma_f32_16x16x32_bf16 v[78:81], v[146:149], v[208:211], v[78:81]
	v_mfma_f32_16x16x32_bf16 v[74:77], v[154:157], v[208:211], v[74:77]
	v_mfma_f32_16x16x32_bf16 v[126:129], v[150:153], v[188:191], v[126:129]
	v_mfma_f32_16x16x32_bf16 v[122:125], v[164:167], v[188:191], v[122:125]
	v_mfma_f32_16x16x32_bf16 v[110:113], v[150:153], v[196:199], v[110:113]
	v_mfma_f32_16x16x32_bf16 v[106:109], v[164:167], v[196:199], v[106:109]
	v_mfma_f32_16x16x32_bf16 v[94:97], v[150:153], v[204:207], v[94:97]
	v_mfma_f32_16x16x32_bf16 v[90:93], v[164:167], v[204:207], v[90:93]
	v_mfma_f32_16x16x32_bf16 v[78:81], v[150:153], v[212:215], v[78:81]
	v_mfma_f32_16x16x32_bf16 v[74:77], v[164:167], v[212:215], v[74:77]
	s_setprio 0
	s_setprio 1
	v_mfma_f32_16x16x32_bf16 v[118:121], v[168:171], v[184:187], v[118:121]
	v_mfma_f32_16x16x32_bf16 v[114:117], v[176:179], v[184:187], v[114:117]
	v_mfma_f32_16x16x32_bf16 v[102:105], v[168:171], v[192:195], v[102:105]
	v_mfma_f32_16x16x32_bf16 v[98:101], v[176:179], v[192:195], v[98:101]
	v_mfma_f32_16x16x32_bf16 v[86:89], v[168:171], v[200:203], v[86:89]
	v_mfma_f32_16x16x32_bf16 v[82:85], v[176:179], v[200:203], v[82:85]
	v_mfma_f32_16x16x32_bf16 v[70:73], v[168:171], v[208:211], v[70:73]
	v_mfma_f32_16x16x32_bf16 v[66:69], v[176:179], v[208:211], v[66:69]
	v_mfma_f32_16x16x32_bf16 v[118:121], v[172:175], v[188:191], v[118:121]
	v_mfma_f32_16x16x32_bf16 v[114:117], v[180:183], v[188:191], v[114:117]
	v_mfma_f32_16x16x32_bf16 v[102:105], v[172:175], v[196:199], v[102:105]
	v_mfma_f32_16x16x32_bf16 v[98:101], v[180:183], v[196:199], v[98:101]
	v_mfma_f32_16x16x32_bf16 v[86:89], v[172:175], v[204:207], v[86:89]
	v_mfma_f32_16x16x32_bf16 v[82:85], v[180:183], v[204:207], v[82:85]
	v_mfma_f32_16x16x32_bf16 v[70:73], v[172:175], v[212:215], v[70:73]
	v_mfma_f32_16x16x32_bf16 v[66:69], v[180:183], v[212:215], v[66:69]
	s_setprio 0
	s_barrier
	s_add_i32 s87, s69, s55
	v_lshl_add_u64 v[216:217], s[48:49], 0, v[136:137]
	s_mov_b32 m0, s87
	ds_read_b128 v[184:187], v162 offset:16384
	ds_read_b128 v[188:191], v162 offset:17408
	ds_read_b128 v[192:195], v162 offset:18432
	ds_read_b128 v[196:199], v162 offset:19456
	ds_read_b128 v[200:203], v162 offset:20480
	ds_read_b128 v[204:207], v162 offset:21504
	ds_read_b128 v[208:211], v162 offset:22528
	ds_read_b128 v[212:215], v162 offset:23552
	global_load_lds_dwordx4 v[216:217], off
	s_add_i32 m0, s87, 0x2000
	s_add_u32 s88, s48, 0x40000
	v_lshl_add_u64 v[218:219], s[48:49], 0, v[140:141]
	s_addc_u32 s89, s49, 0
	s_add_i32 s87, s70, s55
	global_load_lds_dwordx4 v[218:219], off
	v_lshl_add_u64 v[220:221], s[88:89], 0, v[136:137]
	s_mov_b32 m0, s87
	v_lshl_add_u64 v[222:223], s[50:51], 0, v[138:139]
	global_load_lds_dwordx4 v[220:221], off
	v_lshl_add_u64 v[220:221], s[88:89], 0, v[140:141]
	s_add_i32 m0, s87, 0x2000
	s_nop 0
	global_load_lds_dwordx4 v[220:221], off
	v_lshl_add_u64 v[220:221], s[50:51], 0, v[134:135]
	s_mov_b32 m0, s56
	s_nop 0
	global_load_lds_dwordx4 v[220:221], off
	s_mov_b32 m0, s57
	s_nop 0
	global_load_lds_dwordx4 v[222:223], off
	s_waitcnt vmcnt(8)
	s_waitcnt lgkmcnt(0)
	s_barrier
	s_setprio 1
	s_waitcnt lgkmcnt(0)
	v_mfma_f32_16x16x32_bf16 v[62:65], v[146:149], v[184:187], v[62:65]
	v_mfma_f32_16x16x32_bf16 v[58:61], v[154:157], v[184:187], v[58:61]
	v_mfma_f32_16x16x32_bf16 v[46:49], v[146:149], v[192:195], v[46:49]
	v_mfma_f32_16x16x32_bf16 v[42:45], v[154:157], v[192:195], v[42:45]
	v_mfma_f32_16x16x32_bf16 v[6:9], v[146:149], v[200:203], v[6:9]
	v_mfma_f32_16x16x32_bf16 v[2:5], v[154:157], v[200:203], v[2:5]
	v_mfma_f32_16x16x32_bf16 v[22:25], v[146:149], v[208:211], v[22:25]
	v_mfma_f32_16x16x32_bf16 v[18:21], v[154:157], v[208:211], v[18:21]
	v_mfma_f32_16x16x32_bf16 v[62:65], v[150:153], v[188:191], v[62:65]
	v_mfma_f32_16x16x32_bf16 v[58:61], v[164:167], v[188:191], v[58:61]
	v_mfma_f32_16x16x32_bf16 v[46:49], v[150:153], v[196:199], v[46:49]
	v_mfma_f32_16x16x32_bf16 v[42:45], v[164:167], v[196:199], v[42:45]
	v_mfma_f32_16x16x32_bf16 v[6:9], v[150:153], v[204:207], v[6:9]
	v_mfma_f32_16x16x32_bf16 v[2:5], v[164:167], v[204:207], v[2:5]
	v_mfma_f32_16x16x32_bf16 v[22:25], v[150:153], v[212:215], v[22:25]
	v_mfma_f32_16x16x32_bf16 v[18:21], v[164:167], v[212:215], v[18:21]
	s_setprio 0
	s_setprio 1
	v_mfma_f32_16x16x32_bf16 v[54:57], v[168:171], v[184:187], v[54:57]
	v_mfma_f32_16x16x32_bf16 v[50:53], v[176:179], v[184:187], v[50:53]
	v_mfma_f32_16x16x32_bf16 v[38:41], v[168:171], v[192:195], v[38:41]
	v_mfma_f32_16x16x32_bf16 v[34:37], v[176:179], v[192:195], v[34:37]
	v_mfma_f32_16x16x32_bf16 v[14:17], v[168:171], v[200:203], v[14:17]
	v_mfma_f32_16x16x32_bf16 v[10:13], v[176:179], v[200:203], v[10:13]
	v_mfma_f32_16x16x32_bf16 v[30:33], v[168:171], v[208:211], v[30:33]
	v_mfma_f32_16x16x32_bf16 v[26:29], v[176:179], v[208:211], v[26:29]
	v_mfma_f32_16x16x32_bf16 v[54:57], v[172:175], v[188:191], v[54:57]
	v_mfma_f32_16x16x32_bf16 v[50:53], v[180:183], v[188:191], v[50:53]
	v_mfma_f32_16x16x32_bf16 v[38:41], v[172:175], v[196:199], v[38:41]
	v_mfma_f32_16x16x32_bf16 v[34:37], v[180:183], v[196:199], v[34:37]
	v_mfma_f32_16x16x32_bf16 v[14:17], v[172:175], v[204:207], v[14:17]
	v_mfma_f32_16x16x32_bf16 v[10:13], v[180:183], v[204:207], v[10:13]
	v_mfma_f32_16x16x32_bf16 v[30:33], v[172:175], v[212:215], v[30:33]
	v_mfma_f32_16x16x32_bf16 v[26:29], v[180:183], v[212:215], v[26:29]
	s_setprio 0
	s_barrier
	s_add_i32 s87, 0, 0x18000
	v_add_u32_e32 v163, s87, v159
	s_add_i32 s88, 0, 0x1c000
	ds_read_b128 v[146:149], v163
	ds_read_b128 v[150:153], v163 offset:1024
	ds_read_b128 v[154:157], v163 offset:2048
	ds_read_b128 v[164:167], v163 offset:3072
	v_add_u32_e32 v163, s88, v159
	ds_read_b128 v[168:171], v163
	ds_read_b128 v[172:175], v163 offset:1024
	ds_read_b128 v[176:179], v163 offset:2048
	ds_read_b128 v[180:183], v163 offset:3072
	s_add_u32 s50, s50, 0x40000
	s_addc_u32 s51, s51, 0
	s_mov_b32 m0, s58
	v_lshl_add_u64 v[224:225], s[50:51], 0, v[134:135]
	ds_read_b128 v[184:187], v162 offset:32768
	ds_read_b128 v[188:191], v162 offset:33792
	ds_read_b128 v[192:195], v162 offset:34816
	ds_read_b128 v[196:199], v162 offset:35840
	ds_read_b128 v[200:203], v162 offset:36864
	ds_read_b128 v[204:207], v162 offset:37888
	ds_read_b128 v[208:211], v162 offset:38912
	ds_read_b128 v[212:215], v162 offset:39936
	global_load_lds_dwordx4 v[224:225], off
	v_lshl_add_u64 v[224:225], s[50:51], 0, v[138:139]
	s_mov_b32 m0, s59
	s_nop 0
	global_load_lds_dwordx4 v[224:225], off
	s_waitcnt vmcnt(8)
	s_waitcnt lgkmcnt(0)
	s_barrier
	s_setprio 1
	s_waitcnt lgkmcnt(0)
	v_mfma_f32_16x16x32_bf16 v[126:129], v[146:149], v[184:187], v[126:129]
	v_mfma_f32_16x16x32_bf16 v[122:125], v[154:157], v[184:187], v[122:125]
	v_mfma_f32_16x16x32_bf16 v[110:113], v[146:149], v[192:195], v[110:113]
	v_mfma_f32_16x16x32_bf16 v[106:109], v[154:157], v[192:195], v[106:109]
	v_mfma_f32_16x16x32_bf16 v[94:97], v[146:149], v[200:203], v[94:97]
	v_mfma_f32_16x16x32_bf16 v[90:93], v[154:157], v[200:203], v[90:93]
	v_mfma_f32_16x16x32_bf16 v[78:81], v[146:149], v[208:211], v[78:81]
	v_mfma_f32_16x16x32_bf16 v[74:77], v[154:157], v[208:211], v[74:77]
	v_mfma_f32_16x16x32_bf16 v[126:129], v[150:153], v[188:191], v[126:129]
	v_mfma_f32_16x16x32_bf16 v[122:125], v[164:167], v[188:191], v[122:125]
	v_mfma_f32_16x16x32_bf16 v[110:113], v[150:153], v[196:199], v[110:113]
	v_mfma_f32_16x16x32_bf16 v[106:109], v[164:167], v[196:199], v[106:109]
	v_mfma_f32_16x16x32_bf16 v[94:97], v[150:153], v[204:207], v[94:97]
	v_mfma_f32_16x16x32_bf16 v[90:93], v[164:167], v[204:207], v[90:93]
	v_mfma_f32_16x16x32_bf16 v[78:81], v[150:153], v[212:215], v[78:81]
	v_mfma_f32_16x16x32_bf16 v[74:77], v[164:167], v[212:215], v[74:77]
	s_setprio 0
	s_setprio 1
	v_mfma_f32_16x16x32_bf16 v[118:121], v[168:171], v[184:187], v[118:121]
	v_mfma_f32_16x16x32_bf16 v[114:117], v[176:179], v[184:187], v[114:117]
	v_mfma_f32_16x16x32_bf16 v[102:105], v[168:171], v[192:195], v[102:105]
	v_mfma_f32_16x16x32_bf16 v[98:101], v[176:179], v[192:195], v[98:101]
	v_mfma_f32_16x16x32_bf16 v[86:89], v[168:171], v[200:203], v[86:89]
	v_mfma_f32_16x16x32_bf16 v[82:85], v[176:179], v[200:203], v[82:85]
	v_mfma_f32_16x16x32_bf16 v[70:73], v[168:171], v[208:211], v[70:73]
	v_mfma_f32_16x16x32_bf16 v[66:69], v[176:179], v[208:211], v[66:69]
	v_mfma_f32_16x16x32_bf16 v[118:121], v[172:175], v[188:191], v[118:121]
	v_mfma_f32_16x16x32_bf16 v[114:117], v[180:183], v[188:191], v[114:117]
	v_mfma_f32_16x16x32_bf16 v[102:105], v[172:175], v[196:199], v[102:105]
	v_mfma_f32_16x16x32_bf16 v[98:101], v[180:183], v[196:199], v[98:101]
	v_mfma_f32_16x16x32_bf16 v[86:89], v[172:175], v[204:207], v[86:89]
	v_mfma_f32_16x16x32_bf16 v[82:85], v[180:183], v[204:207], v[82:85]
	v_mfma_f32_16x16x32_bf16 v[70:73], v[172:175], v[212:215], v[70:73]
	v_mfma_f32_16x16x32_bf16 v[66:69], v[180:183], v[212:215], v[66:69]
	s_setprio 0
	s_barrier
	s_cmp_lg_u32 s10, s0
	s_cbranch_scc1 .Lmy_p4_nox
	s_cmp_gt_u32 s78, 7
	s_cbranch_scc1 .Lmy_p4_nox
	s_lshl_b32 s98, s4, 8
	s_add_i32 s98, s98, s62
	v_add_u32_e32 v252, s98, v1
	s_lshl_b32 s98, s78, 8
	s_or_b32 s98, s98, s63
	v_lshl_add_u32 v250, v158, 3, s98
	v_lshlrev_b32_e32 v250, 1, v250
	v_lshl_add_u32 v250, v252, 12, v250
	v_add_u32_e32 v250, 0xfa00000, v250
	s_lshl_b32 s98, s78, 3
	s_and_b32 s98, s98, -16
	s_lshl_b32 s98, s98, 2
	v_lshl_add_u32 v251, v158, 4, s98
	v_lshl_add_u32 v251, v252, 8, v251
	global_load_dwordx4 v[226:229], v250, s[8:9]
	global_load_dwordx4 v[230:233], v251, s[60:61]
	v_add_u32_e32 v253, 0x1000, v251
	global_load_dwordx4 v[234:237], v253, s[60:61]
	global_load_dwordx4 v[238:241], v250, s[8:9] offset:256
	v_add_u32_e32 v250, 0x10000, v250
	global_load_dwordx4 v[242:245], v250, s[8:9]
	global_load_dwordx4 v[246:249], v250, s[8:9] offset:256
.Lmy_p4_nox:
	s_add_i32 s50, s87, s55
	v_lshl_add_u64 v[216:217], v[216:217], 0, s[14:15]
	s_mov_b32 m0, s50
	ds_read_b128 v[184:187], v162 offset:49152
	ds_read_b128 v[188:191], v162 offset:50176
	ds_read_b128 v[192:195], v162 offset:51200
	ds_read_b128 v[196:199], v162 offset:52224
	ds_read_b128 v[200:203], v162 offset:53248
	ds_read_b128 v[204:207], v162 offset:54272
	ds_read_b128 v[208:211], v162 offset:55296
	ds_read_b128 v[212:215], v162 offset:56320
	global_load_lds_dwordx4 v[216:217], off
	s_add_i32 m0, s50, 0x2000
	s_add_u32 s48, s48, 0x40080
	v_lshl_add_u64 v[216:217], v[218:219], 0, s[14:15]
	s_addc_u32 s49, s49, 0
	s_add_i32 s50, s88, s55
	global_load_lds_dwordx4 v[216:217], off
	v_lshl_add_u64 v[216:217], s[48:49], 0, v[136:137]
	s_mov_b32 m0, s50
	s_nop 0
	global_load_lds_dwordx4 v[216:217], off
	v_lshl_add_u64 v[216:217], s[48:49], 0, v[140:141]
	s_add_i32 m0, s50, 0x2000
	s_nop 0
	global_load_lds_dwordx4 v[216:217], off
	v_lshl_add_u64 v[216:217], v[220:221], 0, s[14:15]
	s_mov_b32 m0, s64
	s_nop 0
	global_load_lds_dwordx4 v[216:217], off
	v_lshl_add_u64 v[216:217], v[222:223], 0, s[14:15]
	s_mov_b32 m0, s65
	s_nop 0
	global_load_lds_dwordx4 v[216:217], off
	s_cmp_lg_u32 s10, s0
	s_cbranch_scc1 .Lmy_p4_wd_n
	s_cmp_gt_u32 s78, 7
	s_cbranch_scc1 .Lmy_p4_wd_n
	s_waitcnt vmcnt(14)
	s_branch .Lmy_p4_wd_done

.LBB0_696:
	s_lshl_b32 s4, s78, 3
	s_and_b32 s4, s4, -16
	s_ashr_i32 s5, s4, 31
	s_lshl_b64 s[4:5], s[4:5], 2
	s_add_u32 s4, s60, s4
	s_addc_u32 s5, s61, s5
	v_ashrrev_i32_e32 v149, 31, v148
	v_lshl_add_u64 v[150:151], v[150:151], 1, s[0:1]
	v_lshlrev_b64 v[130:131], 12, v[146:147]
	v_lshl_add_u64 v[154:155], v[150:151], 0, v[130:131]
	v_lshl_add_u64 v[152:153], v[148:149], 4, s[4:5]
	v_lshlrev_b64 v[130:131], 8, v[146:147]
	v_lshl_add_u64 v[130:131], v[152:153], 0, v[130:131]
	s_waitcnt vmcnt(8)
	v_mov_b32_e32 v164, v226
	v_mov_b32_e32 v165, v227
	v_mov_b32_e32 v166, v228
	v_mov_b32_e32 v167, v229
	v_mov_b32_e32 v168, v230
	v_mov_b32_e32 v169, v231
	v_mov_b32_e32 v170, v232
	v_mov_b32_e32 v171, v233
	v_add_u32_e32 v130, 16, v146
	v_ashrrev_i32_e32 v131, 31, v130
	v_lshlrev_b64 v[132:133], 8, v[130:131]
	v_lshl_add_u64 v[132:133], v[152:153], 0, v[132:133]
	v_mov_b32_e32 v172, v234
	v_mov_b32_e32 v173, v235
	v_mov_b32_e32 v174, v236
	v_mov_b32_e32 v175, v237
	v_mov_b32_e32 v176, v238
	v_mov_b32_e32 v177, v239
	v_mov_b32_e32 v178, v240
	v_mov_b32_e32 v179, v241
	v_mul_f32_e32 v132, 0xbfb8aa3b, v126
	v_mul_f32_e32 v135, 0xbfb8aa3b, v127
	v_mul_f32_e32 v133, 0xbfb8aa3b, v122
	v_mul_f32_e32 v156, 0xbfb8aa3b, v129
	v_mul_f32_e32 v157, 0xbfb8aa3b, v125
	v_exp_f32_e32 v163, v132
	v_exp_f32_e32 v135, v135
	v_lshlrev_b64 v[130:131], 12, v[130:131]
	v_exp_f32_e32 v184, v133
	v_exp_f32_e32 v185, v156
	v_exp_f32_e32 v186, v157
	v_lshl_add_u64 v[156:157], v[150:151], 0, v[130:131]
	v_mov_b32_e32 v180, v242
	v_mov_b32_e32 v181, v243
	v_mov_b32_e32 v182, v244
	v_mov_b32_e32 v183, v245
	v_mov_b32_e32 v130, v246
	v_mov_b32_e32 v131, v247
	v_mov_b32_e32 v132, v248
	v_mov_b32_e32 v133, v249
	v_add_f32_e32 v163, 1.0, v163
	v_add_f32_e32 v135, 1.0, v135
	v_add_f32_e32 v187, 1.0, v184
	v_add_f32_e32 v189, 1.0, v185
	v_rcp_f32_e32 v184, v163
	v_rcp_f32_e32 v185, v135
	v_mul_f32_e32 v137, 0xbfb8aa3b, v123
	v_mul_f32_e32 v147, 0xbfb8aa3b, v124
	v_exp_f32_e32 v137, v137
	v_pk_mul_f32 v[184:185], v[126:127], v[184:185]
	v_exp_f32_e32 v147, v147
	v_mov_b64_e32 v[148:149], s[38:39]
	v_mul_f32_e32 v139, 0xbfb8aa3b, v128
	v_exp_f32_e32 v139, v139
	v_add_f32_e32 v137, 1.0, v137
	v_add_f32_e32 v147, 1.0, v147
	v_add_f32_e32 v191, 1.0, v186
	v_rcp_f32_e32 v186, v187
	v_rcp_f32_e32 v187, v137
	v_rcp_f32_e32 v190, v147
	v_rcp_f32_e32 v191, v191
	v_add_f32_e32 v139, 1.0, v139
	v_rcp_f32_e32 v188, v139
	v_rcp_f32_e32 v189, v189
	v_pk_mul_f32 v[124:125], v[124:125], v[190:191]
	v_pk_mul_f32 v[122:123], v[122:123], v[186:187]
	v_pk_mul_f32 v[128:129], v[128:129], v[188:189]
	s_waitcnt vmcnt(8)
	v_lshlrev_b32_e32 v192, 16, v166
	v_mov_b32_e32 v126, v169
	v_mov_b32_e32 v127, v170
	v_mov_b32_e32 v169, v171
	v_pk_add_f32 v[126:127], v[126:127], v[168:169]
	v_and_b32_e32 v193, 0xffff0000, v166
	v_mov_b32_e32 v170, v173
	v_mov_b32_e32 v171, v174
	v_mov_b32_e32 v173, v175
	v_pk_add_f32 v[168:169], v[170:171], v[172:173]
	v_pk_add_f32 v[126:127], v[126:127], v[126:127] op_sel:[0,1] op_sel_hi:[1,0]
	v_pk_add_f32 v[168:169], v[168:169], v[168:169] op_sel:[0,1] op_sel_hi:[1,0]
	v_mov_b32_e32 v127, v126
	v_mov_b32_e32 v135, v168
	s_nop 0
	v_permlane16_swap_b32_e32 v126, v127
	v_permlane16_swap_b32_e32 v168, v135
	v_add_f32_e32 v127, v126, v127
	v_add_f32_e32 v126, v168, v135
	v_mov_b32_e32 v169, v127
	v_mov_b32_e32 v168, v126
	s_nop 0
	v_permlane32_swap_b32_e32 v127, v169
	v_permlane32_swap_b32_e32 v126, v168
	v_pk_add_f32 v[126:127], v[126:127], v[168:169]
	v_lshlrev_b32_e32 v166, 16, v167
	v_pk_fma_f32 v[126:127], v[126:127], s[36:37], v[148:149] op_sel_hi:[1,0,0]
	v_and_b32_e32 v167, 0xffff0000, v167
	v_mul_f32_e32 v135, 0x4b800000, v127
	v_cmp_gt_f32_e32 vcc, s76, v127
	v_pk_mul_f32 v[122:123], v[122:123], v[192:193]
	v_pk_mul_f32 v[124:125], v[124:125], v[166:167]
	v_cndmask_b32_e32 v127, v127, v135, vcc
	v_rsq_f32_e32 v127, v127
	v_lshlrev_b32_e32 v188, 16, v164
	v_and_b32_e32 v189, 0xffff0000, v164
	v_lshlrev_b32_e32 v164, 16, v165
	v_mul_f32_e32 v135, 0x45800000, v127
	v_cndmask_b32_e32 v168, v127, v135, vcc
	v_and_b32_e32 v165, 0xffff0000, v165
	v_pk_mul_f32 v[166:167], v[124:125], v[168:169] op_sel_hi:[1,0]
	v_pk_mul_f32 v[124:125], v[122:123], v[168:169] op_sel_hi:[1,0]
	v_pk_mul_f32 v[128:129], v[128:129], v[164:165]
	v_cvt_pk_bf16_f32 v124, v124, v125
	v_mul_f32_e32 v125, 0xbfb8aa3b, v118
	v_pk_mul_f32 v[128:129], v[128:129], v[168:169] op_sel_hi:[1,0]
	v_exp_f32_e32 v127, v125
	v_mul_f32_e32 v125, 0xbfb8aa3b, v114
	v_cvt_pk_bf16_f32 v123, v128, v129
	v_exp_f32_e32 v129, v125
	v_add_f32_e32 v127, 1.0, v127
	v_mul_f32_e32 v137, 0x4b800000, v126
	v_cmp_gt_f32_e64 s[4:5], s76, v126
	v_rcp_f32_e32 v128, v127
	v_add_f32_e32 v127, 1.0, v129
	v_mul_f32_e32 v129, 0xbfb8aa3b, v119
	v_cndmask_b32_e64 v126, v126, v137, s[4:5]
	v_exp_f32_e32 v129, v129
	v_mul_f32_e32 v135, 0xbfb8aa3b, v115
	v_rsq_f32_e32 v126, v126
	v_exp_f32_e32 v135, v135
	v_pk_mul_f32 v[170:171], v[184:185], v[188:189]
	v_cvt_pk_bf16_f32 v125, v166, v167
	v_pk_mul_f32 v[164:165], v[170:171], v[168:169] op_sel_hi:[1,0]
	v_mul_f32_e32 v137, 0x45800000, v126
	v_cvt_pk_bf16_f32 v122, v164, v165
	v_rcp_f32_e32 v164, v127
	v_add_f32_e32 v127, 1.0, v129
	v_rcp_f32_e32 v129, v127
	v_add_f32_e32 v127, 1.0, v135
	v_mul_f32_e32 v135, 0xbfb8aa3b, v120
	v_cndmask_b32_e64 v126, v126, v137, s[4:5]
	v_exp_f32_e32 v135, v135
	v_mul_f32_e32 v137, 0xbfb8aa3b, v116
	v_exp_f32_e32 v137, v137
	v_rcp_f32_e32 v165, v127
	v_add_f32_e32 v127, 1.0, v135
	v_mul_f32_e32 v135, 0xbfb8aa3b, v121
	v_rcp_f32_e32 v166, v127
	v_add_f32_e32 v127, 1.0, v137
	v_exp_f32_e32 v135, v135
	v_mul_f32_e32 v137, 0xbfb8aa3b, v117
	v_exp_f32_e32 v137, v137
	v_rcp_f32_e32 v170, v127
	v_add_f32_e32 v127, 1.0, v135
	v_rcp_f32_e32 v167, v127
	v_add_f32_e32 v127, 1.0, v137
	v_rcp_f32_e32 v171, v127
	v_lshlrev_b32_e32 v172, 16, v176
	v_and_b32_e32 v173, 0xffff0000, v176
	v_lshlrev_b32_e32 v174, 16, v177
	v_and_b32_e32 v175, 0xffff0000, v177
	v_lshlrev_b32_e32 v176, 16, v178
	v_and_b32_e32 v177, 0xffff0000, v178
	v_lshlrev_b32_e32 v178, 16, v179
	v_and_b32_e32 v179, 0xffff0000, v179
	v_pk_mul_f32 v[116:117], v[116:117], v[170:171]
	v_pk_mul_f32 v[114:115], v[114:115], v[164:165]
	v_pk_mul_f32 v[118:119], v[118:119], v[128:129]
	v_pk_mul_f32 v[114:115], v[114:115], v[176:177]
	v_pk_mul_f32 v[116:117], v[116:117], v[178:179]
	v_pk_mul_f32 v[120:121], v[120:121], v[166:167]
	v_pk_mul_f32 v[118:119], v[118:119], v[172:173]
	v_pk_mul_f32 v[128:129], v[116:117], v[168:169] op_sel_hi:[1,0]
	v_pk_mul_f32 v[116:117], v[114:115], v[168:169] op_sel_hi:[1,0]
	v_pk_mul_f32 v[120:121], v[120:121], v[174:175]
	v_pk_mul_f32 v[118:119], v[118:119], v[168:169] op_sel_hi:[1,0]
	v_cvt_pk_bf16_f32 v116, v116, v117
	v_mul_f32_e32 v117, 0xbfb8aa3b, v110
	v_pk_mul_f32 v[120:121], v[120:121], v[168:169] op_sel_hi:[1,0]
	v_cvt_pk_bf16_f32 v114, v118, v119
	v_exp_f32_e32 v118, v117
	v_mul_f32_e32 v117, 0xbfb8aa3b, v106
	v_cvt_pk_bf16_f32 v115, v120, v121
	v_exp_f32_e32 v119, v117
	v_mul_f32_e32 v120, 0xbfb8aa3b, v111
	v_mul_f32_e32 v121, 0xbfb8aa3b, v107
	v_exp_f32_e32 v120, v120
	v_exp_f32_e32 v121, v121
	v_add_f32_e32 v119, 1.0, v119
	v_cvt_pk_bf16_f32 v117, v128, v129
	v_rcp_f32_e32 v128, v119
	v_add_f32_e32 v119, 1.0, v120
	v_add_f32_e32 v120, 1.0, v121
	v_mul_f32_e32 v121, 0xbfb8aa3b, v112
	v_mul_f32_e32 v127, 0xbfb8aa3b, v108
	v_exp_f32_e32 v121, v121
	v_exp_f32_e32 v127, v127
	v_rcp_f32_e32 v129, v120
	v_add_f32_e32 v118, 1.0, v118
	v_add_f32_e32 v120, 1.0, v121
	v_add_f32_e32 v121, 1.0, v127
	v_mul_f32_e32 v127, 0xbfb8aa3b, v113
	v_exp_f32_e32 v127, v127
	v_rcp_f32_e32 v164, v121
	v_rcp_f32_e32 v118, v118
	v_rcp_f32_e32 v119, v119
	v_add_f32_e32 v121, 1.0, v127
	v_rcp_f32_e32 v120, v120
	v_rcp_f32_e32 v121, v121
	v_add_u32_e32 v174, 48, v146
	v_add_u32_e32 v176, 32, v146
	v_lshlrev_b32_e32 v166, 16, v180
	v_and_b32_e32 v167, 0xffff0000, v180
	v_lshlrev_b32_e32 v168, 16, v181
	v_and_b32_e32 v169, 0xffff0000, v181
	v_pk_mul_f32 v[112:113], v[112:113], v[120:121]
	v_pk_mul_f32 v[110:111], v[110:111], v[118:119]
	v_ashrrev_i32_e32 v175, 31, v174
	v_ashrrev_i32_e32 v177, 31, v176
	v_pk_mul_f32 v[166:167], v[110:111], v[166:167]
	v_pk_mul_f32 v[168:169], v[112:113], v[168:169]
	v_lshlrev_b64 v[110:111], 8, v[174:175]
	v_lshlrev_b64 v[112:113], 8, v[176:177]
	v_lshl_add_u64 v[110:111], v[152:153], 0, v[110:111]
	v_lshl_add_u64 v[118:119], v[152:153], 0, v[112:113]
	global_load_dwordx4 v[110:113], v[110:111], off
	s_nop 0
	global_load_dwordx4 v[118:121], v[118:119], off
	v_mul_f32_e32 v135, 0xbfb8aa3b, v109
	v_exp_f32_e32 v135, v135
	v_lshlrev_b32_e32 v170, 16, v182
	v_and_b32_e32 v171, 0xffff0000, v182
	v_lshlrev_b32_e32 v172, 16, v183
	v_add_f32_e32 v127, 1.0, v135
	v_rcp_f32_e32 v165, v127
	v_and_b32_e32 v173, 0xffff0000, v183
	v_pk_mul_f32 v[106:107], v[106:107], v[128:129]
	v_pk_mul_f32 v[166:167], v[166:167], v[126:127] op_sel_hi:[1,0]
	v_pk_mul_f32 v[108:109], v[108:109], v[164:165]
	v_pk_mul_f32 v[106:107], v[106:107], v[170:171]
	v_pk_mul_f32 v[108:109], v[108:109], v[172:173]
	v_pk_mul_f32 v[106:107], v[106:107], v[126:127] op_sel_hi:[1,0]
	v_pk_mul_f32 v[108:109], v[108:109], v[126:127] op_sel_hi:[1,0]
	v_cvt_pk_bf16_f32 v164, v166, v167
	v_cvt_pk_bf16_f32 v166, v106, v107
	v_mul_f32_e32 v107, 0xbfb8aa3b, v98
	v_cvt_pk_bf16_f32 v167, v108, v109
	v_mul_f32_e32 v108, 0xbfb8aa3b, v103
	v_exp_f32_e32 v107, v107
	v_exp_f32_e32 v109, v108
	v_mul_f32_e32 v108, 0xbfb8aa3b, v99
	v_pk_mul_f32 v[168:169], v[168:169], v[126:127] op_sel_hi:[1,0]
	v_exp_f32_e32 v127, v108
	v_add_f32_e32 v107, 1.0, v107
	v_rcp_f32_e32 v108, v107
	v_add_f32_e32 v107, 1.0, v109
	v_add_f32_e32 v109, 1.0, v127
	v_mul_f32_e32 v127, 0xbfb8aa3b, v104
	v_exp_f32_e32 v127, v127
	v_mul_f32_e32 v128, 0xbfb8aa3b, v100
	v_exp_f32_e32 v129, v128
	v_mul_f32_e32 v106, 0xbfb8aa3b, v102
	v_add_f32_e32 v127, 1.0, v127
	v_rcp_f32_e32 v128, v127
	v_add_f32_e32 v127, 1.0, v129
	v_mul_f32_e32 v129, 0xbfb8aa3b, v105
	v_exp_f32_e32 v129, v129
	v_mul_f32_e32 v135, 0xbfb8aa3b, v101
	v_exp_f32_e32 v106, v106
	v_exp_f32_e32 v135, v135
	v_rcp_f32_e32 v109, v109
	v_cvt_pk_bf16_f32 v165, v168, v169
	v_rcp_f32_e32 v168, v127
	v_add_f32_e32 v127, 1.0, v129
	v_add_f32_e32 v106, 1.0, v106
	v_rcp_f32_e32 v129, v127
	v_add_f32_e32 v127, 1.0, v135
	v_rcp_f32_e32 v106, v106
	v_rcp_f32_e32 v107, v107
	v_rcp_f32_e32 v169, v127
	v_lshlrev_b32_e32 v172, 16, v132
	v_and_b32_e32 v173, 0xffff0000, v132
	v_pk_mul_f32 v[98:99], v[98:99], v[108:109]
	v_pk_mul_f32 v[104:105], v[104:105], v[128:129]
	v_pk_mul_f32 v[98:99], v[98:99], v[172:173]
	v_lshlrev_b32_e32 v170, 16, v130
	v_pk_mul_f32 v[98:99], v[98:99], v[126:127] op_sel_hi:[1,0]
	v_and_b32_e32 v171, 0xffff0000, v130
	v_cvt_pk_bf16_f32 v128, v98, v99
	v_lshlrev_b64 v[98:99], 12, v[176:177]
	v_lshlrev_b32_e32 v130, 16, v131
	v_and_b32_e32 v131, 0xffff0000, v131
	v_lshlrev_b32_e32 v132, 16, v133
	v_and_b32_e32 v133, 0xffff0000, v133
	v_pk_mul_f32 v[102:103], v[102:103], v[106:107]
	v_pk_mul_f32 v[100:101], v[100:101], v[168:169]
	v_lshl_add_u64 v[108:109], v[150:151], 0, v[98:99]
	v_pk_mul_f32 v[102:103], v[102:103], v[170:171]
	v_pk_mul_f32 v[104:105], v[104:105], v[130:131]
	v_pk_mul_f32 v[100:101], v[100:101], v[132:133]
	global_load_dwordx4 v[130:133], v[108:109], off offset:256
	global_load_dwordx4 v[168:171], v[108:109], off
	v_lshlrev_b64 v[98:99], 12, v[174:175]
	v_pk_mul_f32 v[104:105], v[104:105], v[126:127] op_sel_hi:[1,0]
	v_pk_mul_f32 v[102:103], v[102:103], v[126:127] op_sel_hi:[1,0]
	v_pk_mul_f32 v[100:101], v[100:101], v[126:127] op_sel_hi:[1,0]
	v_lshl_add_u64 v[106:107], v[150:151], 0, v[98:99]
	v_cvt_pk_bf16_f32 v126, v102, v103
	v_cvt_pk_bf16_f32 v127, v104, v105
	v_cvt_pk_bf16_f32 v129, v100, v101
	global_load_dwordx4 v[98:101], v[106:107], off offset:256
	global_load_dwordx4 v[102:105], v[106:107], off
	s_nop 0
	global_store_dwordx4 v[154:155], v[122:125], off
	global_store_dwordx4 v[154:155], v[114:117], off offset:256
	global_store_dwordx4 v[156:157], v[164:167], off
	global_store_dwordx4 v[156:157], v[126:129], off offset:256
	s_waitcnt vmcnt(0)
	v_mov_b32_e32 v114, v119
	v_mov_b32_e32 v115, v120
	v_mov_b32_e32 v119, v121
	v_pk_add_f32 v[114:115], v[114:115], v[118:119]
	v_mov_b32_e32 v118, v111
	v_mov_b32_e32 v119, v112
	v_mov_b32_e32 v111, v113
	v_pk_add_f32 v[110:111], v[118:119], v[110:111]
	v_pk_add_f32 v[114:115], v[114:115], v[114:115] op_sel:[0,1] op_sel_hi:[1,0]
	v_pk_add_f32 v[110:111], v[110:111], v[110:111] op_sel:[0,1] op_sel_hi:[1,0]
	v_mov_b32_e32 v115, v114
	v_mov_b32_e32 v111, v110
	s_nop 0
	v_permlane16_swap_b32_e32 v114, v115
	v_permlane16_swap_b32_e32 v110, v111
	v_add_f32_e32 v115, v114, v115
	v_add_f32_e32 v114, v110, v111
	v_mov_b32_e32 v117, v115
	v_mov_b32_e32 v116, v114
	s_nop 0
	v_permlane32_swap_b32_e32 v115, v117
	v_permlane32_swap_b32_e32 v114, v116
	v_pk_add_f32 v[110:111], v[114:115], v[116:117]
	v_mul_f32_e32 v113, 0xbfb8aa3b, v94
	v_pk_fma_f32 v[110:111], v[110:111], s[36:37], v[148:149] op_sel_hi:[1,0,0]
	v_exp_f32_e32 v113, v113
	v_mul_f32_e32 v112, 0x4b800000, v111
	v_cmp_gt_f32_e32 vcc, s76, v111
	v_cmp_gt_f32_e64 s[4:5], s76, v110
	v_mul_f32_e32 v114, 0xbfb8aa3b, v90
	v_cndmask_b32_e32 v111, v111, v112, vcc
	v_mul_f32_e32 v112, 0x4b800000, v110
	v_rsq_f32_e32 v111, v111
	v_cndmask_b32_e64 v110, v110, v112, s[4:5]
	v_rsq_f32_e32 v110, v110
	v_exp_f32_e32 v115, v114
	v_mul_f32_e32 v112, 0x45800000, v111
	v_cndmask_b32_e32 v112, v111, v112, vcc
	v_mul_f32_e32 v111, 0x45800000, v110
	v_cndmask_b32_e64 v110, v110, v111, s[4:5]
	v_add_f32_e32 v111, 1.0, v113
	v_mul_f32_e32 v113, 0xbfb8aa3b, v95
	v_rcp_f32_e32 v114, v111
	v_add_f32_e32 v111, 1.0, v115
	v_exp_f32_e32 v113, v113
	v_mul_f32_e32 v115, 0xbfb8aa3b, v91
	v_exp_f32_e32 v117, v115
	v_rcp_f32_e32 v116, v111
	v_add_f32_e32 v111, 1.0, v113
	v_mul_f32_e32 v113, 0xbfb8aa3b, v96
	v_rcp_f32_e32 v115, v111
	v_add_f32_e32 v111, 1.0, v117
	v_exp_f32_e32 v113, v113
	v_mul_f32_e32 v117, 0xbfb8aa3b, v92
	v_exp_f32_e32 v119, v117
	v_rcp_f32_e32 v117, v111
	v_add_f32_e32 v111, 1.0, v113
	v_mul_f32_e32 v113, 0xbfb8aa3b, v97
	v_rcp_f32_e32 v118, v111
	v_add_f32_e32 v111, 1.0, v119
	v_exp_f32_e32 v113, v113
	v_mul_f32_e32 v119, 0xbfb8aa3b, v93
	v_exp_f32_e32 v121, v119
	v_rcp_f32_e32 v120, v111
	v_add_f32_e32 v111, 1.0, v113
	v_rcp_f32_e32 v119, v111
	v_add_f32_e32 v111, 1.0, v121
	v_rcp_f32_e32 v121, v111
	v_lshlrev_b32_e32 v126, 16, v170
	v_and_b32_e32 v127, 0xffff0000, v170
	v_lshlrev_b32_e32 v128, 16, v171
	v_and_b32_e32 v129, 0xffff0000, v171
	v_pk_mul_f32 v[92:93], v[92:93], v[120:121]
	v_pk_mul_f32 v[90:91], v[90:91], v[116:117]
	v_lshlrev_b32_e32 v122, 16, v168
	v_and_b32_e32 v123, 0xffff0000, v168
	v_lshlrev_b32_e32 v124, 16, v169
	v_and_b32_e32 v125, 0xffff0000, v169
	v_pk_mul_f32 v[96:97], v[96:97], v[118:119]
	v_pk_mul_f32 v[94:95], v[94:95], v[114:115]
	v_pk_mul_f32 v[90:91], v[90:91], v[126:127]
	v_pk_mul_f32 v[92:93], v[92:93], v[128:129]
	v_pk_mul_f32 v[94:95], v[94:95], v[122:123]
	v_pk_mul_f32 v[96:97], v[96:97], v[124:125]
	v_pk_mul_f32 v[114:115], v[92:93], v[112:113] op_sel_hi:[1,0]
	v_pk_mul_f32 v[92:93], v[90:91], v[112:113] op_sel_hi:[1,0]
	v_pk_mul_f32 v[96:97], v[96:97], v[112:113] op_sel_hi:[1,0]
	v_pk_mul_f32 v[94:95], v[94:95], v[112:113] op_sel_hi:[1,0]
	v_cvt_pk_bf16_f32 v92, v92, v93
	v_mul_f32_e32 v93, 0xbfb8aa3b, v86
	v_cvt_pk_bf16_f32 v90, v94, v95
	v_cvt_pk_bf16_f32 v91, v96, v97
	v_exp_f32_e32 v94, v93
	v_mul_f32_e32 v93, 0xbfb8aa3b, v82
	v_mul_f32_e32 v96, 0xbfb8aa3b, v87
	v_exp_f32_e32 v95, v93
	v_exp_f32_e32 v97, v96
	v_mul_f32_e32 v96, 0xbfb8aa3b, v83
	v_exp_f32_e32 v111, v96
	v_add_f32_e32 v95, 1.0, v95
	v_rcp_f32_e32 v96, v95
	v_add_f32_e32 v95, 1.0, v97
	v_add_f32_e32 v97, 1.0, v111
	v_mul_f32_e32 v111, 0xbfb8aa3b, v88
	v_exp_f32_e32 v111, v111
	v_mul_f32_e32 v113, 0xbfb8aa3b, v84
	v_exp_f32_e32 v113, v113
	v_cvt_pk_bf16_f32 v93, v114, v115
	v_add_f32_e32 v111, 1.0, v111
	v_rcp_f32_e32 v114, v111
	v_add_f32_e32 v111, 1.0, v113
	v_mul_f32_e32 v113, 0xbfb8aa3b, v89
	v_exp_f32_e32 v113, v113
	v_mul_f32_e32 v115, 0xbfb8aa3b, v85
	v_exp_f32_e32 v117, v115
	v_rcp_f32_e32 v116, v111
	v_add_f32_e32 v111, 1.0, v113
	v_rcp_f32_e32 v115, v111
	v_add_f32_e32 v111, 1.0, v117
	v_add_f32_e32 v94, 1.0, v94
	v_rcp_f32_e32 v97, v97
	v_rcp_f32_e32 v117, v111
	v_rcp_f32_e32 v94, v94
	v_rcp_f32_e32 v95, v95
	v_lshlrev_b32_e32 v122, 16, v132
	v_and_b32_e32 v123, 0xffff0000, v132
	v_lshlrev_b32_e32 v124, 16, v133
	v_and_b32_e32 v125, 0xffff0000, v133
	v_pk_mul_f32 v[84:85], v[84:85], v[116:117]
	v_pk_mul_f32 v[82:83], v[82:83], v[96:97]
	v_lshlrev_b32_e32 v118, 16, v130
	v_and_b32_e32 v119, 0xffff0000, v130
	v_pk_mul_f32 v[86:87], v[86:87], v[94:95]
	v_pk_mul_f32 v[82:83], v[82:83], v[122:123]
	v_pk_mul_f32 v[84:85], v[84:85], v[124:125]
	v_lshlrev_b32_e32 v120, 16, v131
	v_and_b32_e32 v121, 0xffff0000, v131
	v_pk_mul_f32 v[88:89], v[88:89], v[114:115]
	v_pk_mul_f32 v[86:87], v[86:87], v[118:119]
	v_pk_mul_f32 v[94:95], v[84:85], v[112:113] op_sel_hi:[1,0]
	v_pk_mul_f32 v[84:85], v[82:83], v[112:113] op_sel_hi:[1,0]
	v_pk_mul_f32 v[88:89], v[88:89], v[120:121]
	v_pk_mul_f32 v[86:87], v[86:87], v[112:113] op_sel_hi:[1,0]
	v_cvt_pk_bf16_f32 v84, v84, v85
	v_mul_f32_e32 v85, 0xbfb8aa3b, v78
	v_pk_mul_f32 v[88:89], v[88:89], v[112:113] op_sel_hi:[1,0]
	v_cvt_pk_bf16_f32 v82, v86, v87
	v_exp_f32_e32 v86, v85
	v_mul_f32_e32 v85, 0xbfb8aa3b, v74
	v_cvt_pk_bf16_f32 v83, v88, v89
	v_exp_f32_e32 v87, v85
	v_mul_f32_e32 v88, 0xbfb8aa3b, v79
	v_mul_f32_e32 v89, 0xbfb8aa3b, v75
	v_exp_f32_e32 v88, v88
	v_exp_f32_e32 v89, v89
	v_add_f32_e32 v87, 1.0, v87
	v_cvt_pk_bf16_f32 v85, v94, v95
	v_rcp_f32_e32 v94, v87
	v_add_f32_e32 v87, 1.0, v88
	v_add_f32_e32 v88, 1.0, v89
	v_mul_f32_e32 v89, 0xbfb8aa3b, v80
	v_mul_f32_e32 v95, 0xbfb8aa3b, v76
	v_exp_f32_e32 v89, v89
	v_exp_f32_e32 v96, v95
	v_rcp_f32_e32 v95, v88
	v_add_f32_e32 v86, 1.0, v86
	v_add_f32_e32 v88, 1.0, v89
	v_add_f32_e32 v89, 1.0, v96
	v_mul_f32_e32 v96, 0xbfb8aa3b, v81
	v_exp_f32_e32 v97, v96
	v_mul_f32_e32 v96, 0xbfb8aa3b, v77
	v_exp_f32_e32 v111, v96
	v_rcp_f32_e32 v96, v89
	v_add_f32_e32 v89, 1.0, v97
	v_rcp_f32_e32 v86, v86
	v_rcp_f32_e32 v87, v87
	v_rcp_f32_e32 v88, v88
	v_rcp_f32_e32 v89, v89
	v_add_u32_e32 v116, 0x90, v146
	v_add_u32_e32 v118, 0x80, v146
	v_lshlrev_b32_e32 v112, 16, v102
	v_and_b32_e32 v113, 0xffff0000, v102
	v_lshlrev_b32_e32 v102, 16, v103
	v_and_b32_e32 v103, 0xffff0000, v103
	v_pk_mul_f32 v[80:81], v[80:81], v[88:89]
	v_pk_mul_f32 v[78:79], v[78:79], v[86:87]
	v_ashrrev_i32_e32 v117, 31, v116
	v_ashrrev_i32_e32 v119, 31, v118
	v_pk_mul_f32 v[112:113], v[78:79], v[112:113]
	v_pk_mul_f32 v[102:103], v[80:81], v[102:103]
	v_lshlrev_b64 v[78:79], 8, v[116:117]
	v_lshlrev_b64 v[80:81], 8, v[118:119]
	v_lshl_add_u64 v[78:79], v[152:153], 0, v[78:79]
	v_lshl_add_u64 v[86:87], v[152:153], 0, v[80:81]
	global_load_dwordx4 v[78:81], v[78:79], off
	s_nop 0
	global_load_dwordx4 v[86:89], v[86:87], off
	v_add_f32_e32 v97, 1.0, v111
	v_rcp_f32_e32 v97, v97
	v_lshlrev_b32_e32 v114, 16, v104
	v_and_b32_e32 v115, 0xffff0000, v104
	v_lshlrev_b32_e32 v104, 16, v105
	v_and_b32_e32 v105, 0xffff0000, v105
	v_pk_mul_f32 v[76:77], v[76:77], v[96:97]
	v_pk_mul_f32 v[74:75], v[74:75], v[94:95]
	v_pk_mul_f32 v[76:77], v[76:77], v[104:105]
	v_pk_mul_f32 v[74:75], v[74:75], v[114:115]
	v_pk_mul_f32 v[76:77], v[76:77], v[110:111] op_sel_hi:[1,0]
	v_pk_mul_f32 v[74:75], v[74:75], v[110:111] op_sel_hi:[1,0]
	v_cvt_pk_bf16_f32 v97, v76, v77
	v_cvt_pk_bf16_f32 v96, v74, v75
	v_mul_f32_e32 v75, 0xbfb8aa3b, v66
	v_mul_f32_e32 v76, 0xbfb8aa3b, v71
	v_pk_mul_f32 v[102:103], v[102:103], v[110:111] op_sel_hi:[1,0]
	v_exp_f32_e32 v75, v75
	v_exp_f32_e32 v77, v76
	v_mul_f32_e32 v76, 0xbfb8aa3b, v67
	v_cvt_pk_bf16_f32 v95, v102, v103
	v_exp_f32_e32 v102, v76
	v_mul_f32_e32 v103, 0xbfb8aa3b, v68
	v_mul_f32_e32 v104, 0xbfb8aa3b, v73
	v_add_f32_e32 v75, 1.0, v75
	v_exp_f32_e32 v103, v103
	v_exp_f32_e32 v105, v104
	v_mul_f32_e32 v104, 0xbfb8aa3b, v69
	v_pk_mul_f32 v[112:113], v[112:113], v[110:111] op_sel_hi:[1,0]
	v_mul_f32_e32 v74, 0xbfb8aa3b, v70
	v_rcp_f32_e32 v76, v75
	v_add_f32_e32 v75, 1.0, v77
	v_add_f32_e32 v77, 1.0, v102
	v_mul_f32_e32 v102, 0xbfb8aa3b, v72
	v_exp_f32_e32 v111, v104
	v_exp_f32_e32 v74, v74
	v_exp_f32_e32 v102, v102
	v_rcp_f32_e32 v77, v77
	v_add_f32_e32 v103, 1.0, v103
	v_rcp_f32_e32 v104, v103
	v_add_f32_e32 v103, 1.0, v105
	v_add_f32_e32 v105, 1.0, v111
	v_add_f32_e32 v74, 1.0, v74
	v_add_f32_e32 v102, 1.0, v102
	v_rcp_f32_e32 v105, v105
	v_rcp_f32_e32 v74, v74
	v_rcp_f32_e32 v75, v75
	v_rcp_f32_e32 v102, v102
	v_rcp_f32_e32 v103, v103
	v_lshlrev_b32_e32 v114, 16, v100
	v_and_b32_e32 v115, 0xffff0000, v100
	v_pk_mul_f32 v[66:67], v[66:67], v[76:77]
	v_lshlrev_b32_e32 v100, 16, v101
	v_pk_mul_f32 v[66:67], v[66:67], v[114:115]
	v_and_b32_e32 v101, 0xffff0000, v101
	v_pk_mul_f32 v[68:69], v[68:69], v[104:105]
	v_pk_mul_f32 v[66:67], v[66:67], v[110:111] op_sel_hi:[1,0]
	v_cvt_pk_bf16_f32 v94, v112, v113
	v_lshlrev_b32_e32 v112, 16, v98
	v_and_b32_e32 v113, 0xffff0000, v98
	v_lshlrev_b32_e32 v98, 16, v99
	v_and_b32_e32 v99, 0xffff0000, v99
	v_pk_mul_f32 v[72:73], v[72:73], v[102:103]
	v_pk_mul_f32 v[70:71], v[70:71], v[74:75]
	v_pk_mul_f32 v[68:69], v[68:69], v[100:101]
	v_cvt_pk_bf16_f32 v100, v66, v67
	v_lshlrev_b64 v[66:67], 12, v[118:119]
	v_pk_mul_f32 v[70:71], v[70:71], v[112:113]
	v_pk_mul_f32 v[72:73], v[72:73], v[98:99]
	v_lshl_add_u64 v[74:75], v[150:151], 0, v[66:67]
	v_pk_mul_f32 v[72:73], v[72:73], v[110:111] op_sel_hi:[1,0]
	v_pk_mul_f32 v[70:71], v[70:71], v[110:111] op_sel_hi:[1,0]
	v_pk_mul_f32 v[68:69], v[68:69], v[110:111] op_sel_hi:[1,0]
	global_load_dwordx4 v[102:105], v[74:75], off offset:256
	global_load_dwordx4 v[110:113], v[74:75], off
	v_lshlrev_b64 v[66:67], 12, v[116:117]
	v_lshl_add_u64 v[76:77], v[150:151], 0, v[66:67]
	v_cvt_pk_bf16_f32 v98, v70, v71
	v_cvt_pk_bf16_f32 v99, v72, v73
	v_cvt_pk_bf16_f32 v101, v68, v69
	global_load_dwordx4 v[66:69], v[76:77], off offset:256
	global_load_dwordx4 v[70:73], v[76:77], off
	s_nop 0
	global_store_dwordx4 v[108:109], v[90:93], off
	global_store_dwordx4 v[108:109], v[82:85], off offset:256
	global_store_dwordx4 v[106:107], v[94:97], off
	global_store_dwordx4 v[106:107], v[98:101], off offset:256
	s_waitcnt vmcnt(0)
	v_mov_b32_e32 v82, v87
	v_mov_b32_e32 v83, v88
	v_mov_b32_e32 v87, v89
	v_pk_add_f32 v[82:83], v[82:83], v[86:87]
	v_mov_b32_e32 v86, v79
	v_mov_b32_e32 v87, v80
	v_mov_b32_e32 v79, v81
	v_pk_add_f32 v[78:79], v[86:87], v[78:79]
	v_pk_add_f32 v[82:83], v[82:83], v[82:83] op_sel:[0,1] op_sel_hi:[1,0]
	v_pk_add_f32 v[78:79], v[78:79], v[78:79] op_sel:[0,1] op_sel_hi:[1,0]
	v_mov_b32_e32 v83, v82
	v_mov_b32_e32 v79, v78
	s_nop 0
	v_permlane16_swap_b32_e32 v82, v83
	v_permlane16_swap_b32_e32 v78, v79
	v_add_f32_e32 v83, v82, v83
	v_add_f32_e32 v82, v78, v79
	v_mov_b32_e32 v85, v83
	v_mov_b32_e32 v84, v82
	s_nop 0
	v_permlane32_swap_b32_e32 v83, v85
	v_permlane32_swap_b32_e32 v82, v84
	v_pk_add_f32 v[78:79], v[82:83], v[84:85]
	v_mul_f32_e32 v81, 0xbfb8aa3b, v62
	v_pk_fma_f32 v[78:79], v[78:79], s[36:37], v[148:149] op_sel_hi:[1,0,0]
	v_exp_f32_e32 v81, v81
	v_mul_f32_e32 v80, 0x4b800000, v79
	v_cmp_gt_f32_e32 vcc, s76, v79
	v_cmp_gt_f32_e64 s[4:5], s76, v78
	v_mul_f32_e32 v82, 0xbfb8aa3b, v58
	v_cndmask_b32_e32 v79, v79, v80, vcc
	v_mul_f32_e32 v80, 0x4b800000, v78
	v_rsq_f32_e32 v79, v79
	v_cndmask_b32_e64 v78, v78, v80, s[4:5]
	v_rsq_f32_e32 v78, v78
	v_exp_f32_e32 v83, v82
	v_mul_f32_e32 v80, 0x45800000, v79
	v_cndmask_b32_e32 v80, v79, v80, vcc
	v_mul_f32_e32 v79, 0x45800000, v78
	v_cndmask_b32_e64 v78, v78, v79, s[4:5]
	v_add_f32_e32 v79, 1.0, v81
	v_mul_f32_e32 v81, 0xbfb8aa3b, v63
	v_rcp_f32_e32 v82, v79
	v_add_f32_e32 v79, 1.0, v83
	v_exp_f32_e32 v81, v81
	v_mul_f32_e32 v83, 0xbfb8aa3b, v59
	v_exp_f32_e32 v85, v83
	v_rcp_f32_e32 v84, v79
	v_add_f32_e32 v79, 1.0, v81
	v_mul_f32_e32 v81, 0xbfb8aa3b, v64
	v_rcp_f32_e32 v83, v79
	v_add_f32_e32 v79, 1.0, v85
	v_exp_f32_e32 v81, v81
	v_mul_f32_e32 v85, 0xbfb8aa3b, v60
	v_exp_f32_e32 v87, v85
	v_rcp_f32_e32 v85, v79
	v_add_f32_e32 v79, 1.0, v81
	v_mul_f32_e32 v81, 0xbfb8aa3b, v65
	v_rcp_f32_e32 v86, v79
	v_add_f32_e32 v79, 1.0, v87
	v_exp_f32_e32 v81, v81
	v_mul_f32_e32 v87, 0xbfb8aa3b, v61
	v_exp_f32_e32 v89, v87
	v_rcp_f32_e32 v88, v79
	v_add_f32_e32 v79, 1.0, v81
	v_rcp_f32_e32 v87, v79
	v_add_f32_e32 v79, 1.0, v89
	v_rcp_f32_e32 v89, v79
	v_pk_mul_f32 v[58:59], v[58:59], v[84:85]
	v_lshlrev_b32_e32 v94, 16, v112
	v_and_b32_e32 v95, 0xffff0000, v112
	v_lshlrev_b32_e32 v96, 16, v113
	v_and_b32_e32 v97, 0xffff0000, v113
	v_pk_mul_f32 v[60:61], v[60:61], v[88:89]
	v_lshlrev_b32_e32 v90, 16, v110
	v_and_b32_e32 v91, 0xffff0000, v110
	v_lshlrev_b32_e32 v92, 16, v111
	v_and_b32_e32 v93, 0xffff0000, v111
	v_pk_mul_f32 v[64:65], v[64:65], v[86:87]
	v_pk_mul_f32 v[62:63], v[62:63], v[82:83]
	v_pk_mul_f32 v[58:59], v[58:59], v[94:95]
	v_pk_mul_f32 v[60:61], v[60:61], v[96:97]
	v_pk_mul_f32 v[62:63], v[62:63], v[90:91]
	v_pk_mul_f32 v[64:65], v[64:65], v[92:93]
	v_pk_mul_f32 v[82:83], v[60:61], v[80:81] op_sel_hi:[1,0]
	v_pk_mul_f32 v[60:61], v[58:59], v[80:81] op_sel_hi:[1,0]
	v_pk_mul_f32 v[64:65], v[64:65], v[80:81] op_sel_hi:[1,0]
	v_pk_mul_f32 v[62:63], v[62:63], v[80:81] op_sel_hi:[1,0]
	v_cvt_pk_bf16_f32 v60, v60, v61
	v_mul_f32_e32 v61, 0xbfb8aa3b, v54
	v_cvt_pk_bf16_f32 v58, v62, v63
	v_cvt_pk_bf16_f32 v59, v64, v65
	v_exp_f32_e32 v62, v61
	v_mul_f32_e32 v61, 0xbfb8aa3b, v50
	v_mul_f32_e32 v64, 0xbfb8aa3b, v55
	v_exp_f32_e32 v63, v61
	v_exp_f32_e32 v65, v64
	v_mul_f32_e32 v64, 0xbfb8aa3b, v51
	v_exp_f32_e32 v79, v64
	v_add_f32_e32 v63, 1.0, v63
	v_rcp_f32_e32 v64, v63
	v_add_f32_e32 v63, 1.0, v65
	v_add_f32_e32 v65, 1.0, v79
	v_mul_f32_e32 v79, 0xbfb8aa3b, v56
	v_exp_f32_e32 v79, v79
	v_mul_f32_e32 v81, 0xbfb8aa3b, v52
	v_exp_f32_e32 v81, v81
	v_cvt_pk_bf16_f32 v61, v82, v83
	v_add_f32_e32 v79, 1.0, v79
	v_rcp_f32_e32 v82, v79
	v_add_f32_e32 v79, 1.0, v81
	v_mul_f32_e32 v81, 0xbfb8aa3b, v57
	v_exp_f32_e32 v81, v81
	v_mul_f32_e32 v83, 0xbfb8aa3b, v53
	v_exp_f32_e32 v85, v83
	v_rcp_f32_e32 v84, v79
	v_add_f32_e32 v79, 1.0, v81
	v_rcp_f32_e32 v83, v79
	v_add_f32_e32 v79, 1.0, v85
	v_add_f32_e32 v62, 1.0, v62
	v_rcp_f32_e32 v65, v65
	v_rcp_f32_e32 v85, v79
	v_rcp_f32_e32 v62, v62
	v_rcp_f32_e32 v63, v63
	v_lshlrev_b32_e32 v90, 16, v104
	v_and_b32_e32 v91, 0xffff0000, v104
	v_lshlrev_b32_e32 v92, 16, v105
	v_and_b32_e32 v93, 0xffff0000, v105
	v_pk_mul_f32 v[52:53], v[52:53], v[84:85]
	v_pk_mul_f32 v[50:51], v[50:51], v[64:65]
	v_lshlrev_b32_e32 v86, 16, v102
	v_and_b32_e32 v87, 0xffff0000, v102
	v_pk_mul_f32 v[54:55], v[54:55], v[62:63]
	v_pk_mul_f32 v[50:51], v[50:51], v[90:91]
	v_pk_mul_f32 v[52:53], v[52:53], v[92:93]
	v_lshlrev_b32_e32 v88, 16, v103
	v_and_b32_e32 v89, 0xffff0000, v103
	v_pk_mul_f32 v[56:57], v[56:57], v[82:83]
	v_pk_mul_f32 v[54:55], v[54:55], v[86:87]
	v_pk_mul_f32 v[62:63], v[52:53], v[80:81] op_sel_hi:[1,0]
	v_pk_mul_f32 v[52:53], v[50:51], v[80:81] op_sel_hi:[1,0]
	v_pk_mul_f32 v[56:57], v[56:57], v[88:89]
	v_pk_mul_f32 v[54:55], v[54:55], v[80:81] op_sel_hi:[1,0]
	v_cvt_pk_bf16_f32 v52, v52, v53
	v_mul_f32_e32 v53, 0xbfb8aa3b, v46
	v_pk_mul_f32 v[56:57], v[56:57], v[80:81] op_sel_hi:[1,0]
	v_cvt_pk_bf16_f32 v50, v54, v55
	v_exp_f32_e32 v54, v53
	v_mul_f32_e32 v53, 0xbfb8aa3b, v42
	v_cvt_pk_bf16_f32 v51, v56, v57
	v_exp_f32_e32 v55, v53
	v_mul_f32_e32 v56, 0xbfb8aa3b, v47
	v_mul_f32_e32 v57, 0xbfb8aa3b, v43
	v_exp_f32_e32 v56, v56
	v_exp_f32_e32 v57, v57
	v_add_f32_e32 v55, 1.0, v55
	v_cvt_pk_bf16_f32 v53, v62, v63
	v_rcp_f32_e32 v62, v55
	v_add_f32_e32 v55, 1.0, v56
	v_add_f32_e32 v56, 1.0, v57
	v_mul_f32_e32 v57, 0xbfb8aa3b, v48
	v_mul_f32_e32 v63, 0xbfb8aa3b, v44
	v_exp_f32_e32 v57, v57
	v_exp_f32_e32 v64, v63
	v_rcp_f32_e32 v63, v56
	v_add_f32_e32 v54, 1.0, v54
	v_add_f32_e32 v56, 1.0, v57
	v_add_f32_e32 v57, 1.0, v64
	v_mul_f32_e32 v64, 0xbfb8aa3b, v49
	v_exp_f32_e32 v65, v64
	v_mul_f32_e32 v64, 0xbfb8aa3b, v45
	v_exp_f32_e32 v79, v64
	v_rcp_f32_e32 v64, v57
	v_add_f32_e32 v57, 1.0, v65
	v_rcp_f32_e32 v54, v54
	v_rcp_f32_e32 v55, v55
	v_rcp_f32_e32 v56, v56
	v_rcp_f32_e32 v57, v57
	v_lshlrev_b32_e32 v80, 16, v70
	v_and_b32_e32 v81, 0xffff0000, v70
	v_lshlrev_b32_e32 v70, 16, v71
	v_and_b32_e32 v71, 0xffff0000, v71
	v_pk_mul_f32 v[48:49], v[48:49], v[56:57]
	v_pk_mul_f32 v[46:47], v[46:47], v[54:55]
	v_add_u32_e32 v84, 0xb0, v146
	v_add_u32_e32 v86, 0xa0, v146
	v_pk_mul_f32 v[80:81], v[46:47], v[80:81]
	v_pk_mul_f32 v[46:47], v[48:49], v[70:71]
	v_ashrrev_i32_e32 v85, 31, v84
	v_ashrrev_i32_e32 v87, 31, v86
	v_pk_mul_f32 v[70:71], v[46:47], v[78:79] op_sel_hi:[1,0]
	v_lshlrev_b64 v[46:47], 8, v[84:85]
	v_lshlrev_b64 v[48:49], 8, v[86:87]
	v_lshl_add_u64 v[46:47], v[152:153], 0, v[46:47]
	v_lshl_add_u64 v[54:55], v[152:153], 0, v[48:49]
	global_load_dwordx4 v[46:49], v[46:47], off
	s_nop 0
	global_load_dwordx4 v[54:57], v[54:55], off
	v_add_f32_e32 v65, 1.0, v79
	v_rcp_f32_e32 v65, v65
	v_lshlrev_b32_e32 v82, 16, v72
	v_and_b32_e32 v83, 0xffff0000, v72
	v_lshlrev_b32_e32 v72, 16, v73
	v_and_b32_e32 v73, 0xffff0000, v73
	v_pk_mul_f32 v[44:45], v[44:45], v[64:65]
	v_pk_mul_f32 v[42:43], v[42:43], v[62:63]
	v_pk_mul_f32 v[44:45], v[44:45], v[72:73]
	v_pk_mul_f32 v[42:43], v[42:43], v[82:83]
	v_pk_mul_f32 v[44:45], v[44:45], v[78:79] op_sel_hi:[1,0]
	v_pk_mul_f32 v[42:43], v[42:43], v[78:79] op_sel_hi:[1,0]
	v_cvt_pk_bf16_f32 v65, v44, v45
	v_cvt_pk_bf16_f32 v64, v42, v43
	v_mul_f32_e32 v43, 0xbfb8aa3b, v34
	v_mul_f32_e32 v44, 0xbfb8aa3b, v39
	v_exp_f32_e32 v43, v43
	v_exp_f32_e32 v45, v44
	v_mul_f32_e32 v44, 0xbfb8aa3b, v35
	v_cvt_pk_bf16_f32 v63, v70, v71
	v_exp_f32_e32 v70, v44
	v_add_f32_e32 v43, 1.0, v43
	v_rcp_f32_e32 v44, v43
	v_add_f32_e32 v43, 1.0, v45
	v_add_f32_e32 v45, 1.0, v70
	v_mul_f32_e32 v70, 0xbfb8aa3b, v40
	v_exp_f32_e32 v70, v70
	v_mul_f32_e32 v71, 0xbfb8aa3b, v36
	v_exp_f32_e32 v71, v71
	v_pk_mul_f32 v[80:81], v[80:81], v[78:79] op_sel_hi:[1,0]
	v_add_f32_e32 v70, 1.0, v70
	v_cvt_pk_bf16_f32 v62, v80, v81
	v_rcp_f32_e32 v80, v70
	v_add_f32_e32 v70, 1.0, v71
	v_rcp_f32_e32 v82, v70
	v_mul_f32_e32 v70, 0xbfb8aa3b, v41
	v_exp_f32_e32 v79, v70
	v_mul_f32_e32 v70, 0xbfb8aa3b, v37
	v_exp_f32_e32 v83, v70
	v_lshlrev_b64 v[70:71], 12, v[84:85]
	v_lshl_add_u64 v[152:153], v[150:151], 0, v[70:71]
	global_load_dwordx4 v[70:73], v[152:153], off offset:256
	v_mul_f32_e32 v42, 0xbfb8aa3b, v38
	v_exp_f32_e32 v42, v42
	v_add_f32_e32 v79, 1.0, v79
	v_rcp_f32_e32 v81, v79
	v_add_f32_e32 v79, 1.0, v83
	v_add_f32_e32 v42, 1.0, v42
	v_rcp_f32_e32 v42, v42
	v_rcp_f32_e32 v43, v43
	v_rcp_f32_e32 v45, v45
	v_rcp_f32_e32 v83, v79
	v_lshlrev_b32_e32 v84, 16, v66
	v_and_b32_e32 v85, 0xffff0000, v66
	v_lshlrev_b32_e32 v66, 16, v67
	v_and_b32_e32 v67, 0xffff0000, v67
	v_lshlrev_b32_e32 v88, 16, v68
	v_and_b32_e32 v89, 0xffff0000, v68
	v_lshlrev_b32_e32 v68, 16, v69
	v_and_b32_e32 v69, 0xffff0000, v69
	v_pk_mul_f32 v[40:41], v[40:41], v[80:81]
	v_pk_mul_f32 v[38:39], v[38:39], v[42:43]
	v_pk_mul_f32 v[36:37], v[36:37], v[82:83]
	v_pk_mul_f32 v[34:35], v[34:35], v[44:45]
	v_pk_mul_f32 v[38:39], v[38:39], v[84:85]
	v_pk_mul_f32 v[40:41], v[40:41], v[66:67]
	v_pk_mul_f32 v[34:35], v[34:35], v[88:89]
	v_pk_mul_f32 v[36:37], v[36:37], v[68:69]
	v_pk_mul_f32 v[40:41], v[40:41], v[78:79] op_sel_hi:[1,0]
	v_pk_mul_f32 v[38:39], v[38:39], v[78:79] op_sel_hi:[1,0]
	v_pk_mul_f32 v[36:37], v[36:37], v[78:79] op_sel_hi:[1,0]
	v_pk_mul_f32 v[34:35], v[34:35], v[78:79] op_sel_hi:[1,0]
	global_load_dwordx4 v[78:81], v[152:153], off
	v_cvt_pk_bf16_f32 v68, v34, v35
	v_lshlrev_b64 v[34:35], 12, v[86:87]
	v_lshl_add_u64 v[42:43], v[150:151], 0, v[34:35]
	v_cvt_pk_bf16_f32 v66, v38, v39
	v_cvt_pk_bf16_f32 v67, v40, v41
	v_cvt_pk_bf16_f32 v69, v36, v37
	global_load_dwordx4 v[38:41], v[42:43], off offset:256
	global_load_dwordx4 v[34:37], v[42:43], off
	s_nop 0
	global_store_dwordx4 v[74:75], v[58:61], off
	global_store_dwordx4 v[74:75], v[50:53], off offset:256
	global_store_dwordx4 v[76:77], v[62:65], off
	global_store_dwordx4 v[76:77], v[66:69], off offset:256
	s_waitcnt vmcnt(0)
	v_mov_b32_e32 v52, v47
	v_mov_b32_e32 v53, v48
	v_mov_b32_e32 v47, v49
	v_mov_b32_e32 v44, v55
	v_mov_b32_e32 v45, v56
	v_mov_b32_e32 v55, v57
	v_pk_add_f32 v[46:47], v[52:53], v[46:47]
	v_pk_add_f32 v[44:45], v[44:45], v[54:55]
	v_pk_add_f32 v[46:47], v[46:47], v[46:47] op_sel:[0,1] op_sel_hi:[1,0]
	v_pk_add_f32 v[44:45], v[44:45], v[44:45] op_sel:[0,1] op_sel_hi:[1,0]
	v_mul_f32_e32 v47, 0xbfb8aa3b, v30
	v_mov_b32_e32 v45, v44
	v_exp_f32_e32 v47, v47
	s_nop 0
	v_permlane16_swap_b32_e32 v44, v45
	v_add_f32_e32 v44, v44, v45
	v_mov_b32_e32 v45, v46
	s_nop 1
	v_permlane16_swap_b32_e32 v46, v45
	v_add_f32_e32 v45, v46, v45
	v_add_f32_e32 v46, 1.0, v47
	v_mul_f32_e32 v47, 0xbfb8aa3b, v31
	v_exp_f32_e32 v47, v47
	v_rcp_f32_e32 v46, v46
	v_mul_f32_e32 v53, 0xbfb8aa3b, v27
	v_exp_f32_e32 v53, v53
	v_add_f32_e32 v47, 1.0, v47
	v_rcp_f32_e32 v47, v47
	v_mul_f32_e32 v54, 0xbfb8aa3b, v28
	v_mul_f32_e32 v55, 0xbfb8aa3b, v29
	v_exp_f32_e32 v54, v54
	v_pk_mul_f32 v[30:31], v[30:31], v[46:47]
	v_mul_f32_e32 v47, 0xbfb8aa3b, v26
	v_exp_f32_e32 v52, v47
	v_exp_f32_e32 v55, v55
	v_add_f32_e32 v53, 1.0, v53
	v_add_f32_e32 v54, 1.0, v54
	v_add_f32_e32 v52, 1.0, v52
	v_rcp_f32_e32 v52, v52
	v_add_f32_e32 v55, 1.0, v55
	v_rcp_f32_e32 v53, v53
	v_rcp_f32_e32 v54, v54
	v_rcp_f32_e32 v55, v55
	v_lshlrev_b32_e32 v46, 16, v70
	v_and_b32_e32 v47, 0xffff0000, v70
	v_pk_mul_f32 v[30:31], v[30:31], v[46:47]
	v_pk_mul_f32 v[26:27], v[26:27], v[52:53]
	v_mul_f32_e32 v47, 0xbfb8aa3b, v22
	v_mul_f32_e32 v53, 0xbfb8aa3b, v23
	v_pk_mul_f32 v[28:29], v[28:29], v[54:55]
	v_exp_f32_e32 v52, v47
	v_exp_f32_e32 v53, v53
	v_mul_f32_e32 v54, 0xbfb8aa3b, v24
	v_mul_f32_e32 v55, 0xbfb8aa3b, v25
	v_mul_f32_e32 v48, 0xbfb8aa3b, v32
	v_mul_f32_e32 v49, 0xbfb8aa3b, v33
	v_exp_f32_e32 v54, v54
	v_exp_f32_e32 v55, v55
	v_exp_f32_e32 v48, v48
	v_exp_f32_e32 v49, v49
	v_add_f32_e32 v52, 1.0, v52
	v_add_f32_e32 v53, 1.0, v53
	v_rcp_f32_e32 v52, v52
	v_add_f32_e32 v54, 1.0, v54
	v_add_f32_e32 v55, 1.0, v55
	v_rcp_f32_e32 v53, v53
	v_add_f32_e32 v48, 1.0, v48
	v_add_f32_e32 v49, 1.0, v49
	v_rcp_f32_e32 v54, v54
	v_rcp_f32_e32 v55, v55
	v_rcp_f32_e32 v48, v48
	v_rcp_f32_e32 v49, v49
	v_lshlrev_b32_e32 v46, 16, v72
	v_and_b32_e32 v47, 0xffff0000, v72
	v_pk_mul_f32 v[26:27], v[26:27], v[46:47]
	v_pk_mul_f32 v[22:23], v[22:23], v[52:53]
	v_mul_f32_e32 v47, 0xbfb8aa3b, v18
	v_mul_f32_e32 v53, 0xbfb8aa3b, v19
	v_mov_b32_e32 v50, v44
	v_mov_b32_e32 v51, v45
	v_pk_mul_f32 v[24:25], v[24:25], v[54:55]
	v_exp_f32_e32 v52, v47
	v_exp_f32_e32 v53, v53
	v_mul_f32_e32 v54, 0xbfb8aa3b, v20
	v_mul_f32_e32 v55, 0xbfb8aa3b, v21
	v_permlane32_swap_b32_e32 v44, v50
	v_permlane32_swap_b32_e32 v45, v51
	v_pk_mul_f32 v[32:33], v[32:33], v[48:49]
	v_lshlrev_b32_e32 v48, 16, v71
	v_and_b32_e32 v49, 0xffff0000, v71
	v_exp_f32_e32 v54, v54
	v_exp_f32_e32 v55, v55
	v_pk_mul_f32 v[32:33], v[32:33], v[48:49]
	v_lshlrev_b32_e32 v48, 16, v73
	v_and_b32_e32 v49, 0xffff0000, v73
	v_pk_add_f32 v[44:45], v[44:45], v[50:51]
	v_pk_mul_f32 v[28:29], v[28:29], v[48:49]
	v_lshlrev_b32_e32 v48, 16, v79
	v_and_b32_e32 v49, 0xffff0000, v79
	v_pk_fma_f32 v[44:45], v[44:45], s[36:37], v[148:149] op_sel_hi:[1,0,0]
	v_add_f32_e32 v52, 1.0, v52
	v_add_f32_e32 v53, 1.0, v53
	v_pk_mul_f32 v[24:25], v[24:25], v[48:49]
	v_mul_f32_e32 v49, 0x4b800000, v45
	v_cmp_gt_f32_e32 vcc, s76, v45
	v_rcp_f32_e32 v52, v52
	v_add_f32_e32 v54, 1.0, v54
	v_add_f32_e32 v55, 1.0, v55
	v_rcp_f32_e32 v53, v53
	v_cndmask_b32_e32 v45, v45, v49, vcc
	v_rcp_f32_e32 v54, v54
	v_rcp_f32_e32 v55, v55
	v_rsq_f32_e32 v45, v45
	v_lshlrev_b32_e32 v46, 16, v78
	v_and_b32_e32 v47, 0xffff0000, v78
	v_pk_mul_f32 v[22:23], v[22:23], v[46:47]
	v_pk_mul_f32 v[18:19], v[18:19], v[52:53]
	v_lshlrev_b32_e32 v46, 16, v80
	v_and_b32_e32 v47, 0xffff0000, v80
	v_pk_mul_f32 v[20:21], v[20:21], v[54:55]
	v_lshlrev_b32_e32 v48, 16, v81
	v_and_b32_e32 v49, 0xffff0000, v81
	v_pk_mul_f32 v[46:47], v[18:19], v[46:47]
	v_mul_f32_e32 v18, 0x45800000, v45
	v_pk_mul_f32 v[20:21], v[20:21], v[48:49]
	v_cndmask_b32_e32 v48, v45, v18, vcc
	v_pk_mul_f32 v[18:19], v[32:33], v[48:49] op_sel_hi:[1,0]
	v_cmp_gt_f32_e32 vcc, s76, v44
	v_cvt_pk_bf16_f32 v131, v18, v19
	v_pk_mul_f32 v[18:19], v[28:29], v[48:49] op_sel_hi:[1,0]
	v_pk_mul_f32 v[26:27], v[26:27], v[48:49] op_sel_hi:[1,0]
	v_cvt_pk_bf16_f32 v133, v18, v19
	v_pk_mul_f32 v[18:19], v[22:23], v[48:49] op_sel_hi:[1,0]
	v_pk_mul_f32 v[22:23], v[20:21], v[48:49] op_sel_hi:[1,0]
	v_pk_mul_f32 v[20:21], v[46:47], v[48:49] op_sel_hi:[1,0]
	v_cvt_pk_bf16_f32 v132, v26, v27
	v_cvt_pk_bf16_f32 v20, v20, v21
	v_cvt_pk_bf16_f32 v21, v22, v23
	v_mul_f32_e32 v23, 0xbfb8aa3b, v14
	v_exp_f32_e32 v23, v23
	v_mul_f32_e32 v22, 0x4b800000, v44
	v_cndmask_b32_e32 v22, v44, v22, vcc
	v_rsq_f32_e32 v26, v22
	v_add_f32_e32 v22, 1.0, v23
	v_mul_f32_e32 v23, 0xbfb8aa3b, v15
	v_exp_f32_e32 v23, v23
	v_pk_mul_f32 v[24:25], v[24:25], v[48:49] op_sel_hi:[1,0]
	v_cvt_pk_bf16_f32 v18, v18, v19
	v_cvt_pk_bf16_f32 v19, v24, v25
	v_add_f32_e32 v23, 1.0, v23
	v_rcp_f32_e32 v22, v22
	v_mul_f32_e32 v24, 0xbfb8aa3b, v16
	v_mul_f32_e32 v25, 0xbfb8aa3b, v17
	v_rcp_f32_e32 v23, v23
	v_exp_f32_e32 v24, v24
	v_exp_f32_e32 v25, v25
	v_mul_f32_e32 v27, 0x45800000, v26
	v_pk_mul_f32 v[14:15], v[14:15], v[22:23]
	v_lshlrev_b32_e32 v22, 16, v38
	v_and_b32_e32 v23, 0xffff0000, v38
	v_add_f32_e32 v24, 1.0, v24
	v_add_f32_e32 v25, 1.0, v25
	v_pk_mul_f32 v[14:15], v[14:15], v[22:23]
	v_mul_f32_e32 v22, 0xbfb8aa3b, v10
	v_mul_f32_e32 v23, 0xbfb8aa3b, v11
	v_rcp_f32_e32 v24, v24
	v_rcp_f32_e32 v25, v25
	v_exp_f32_e32 v22, v22
	v_exp_f32_e32 v23, v23
	v_cndmask_b32_e32 v26, v26, v27, vcc
	v_pk_mul_f32 v[16:17], v[16:17], v[24:25]
	v_lshlrev_b32_e32 v24, 16, v39
	v_and_b32_e32 v25, 0xffff0000, v39
	v_add_f32_e32 v22, 1.0, v22
	v_add_f32_e32 v23, 1.0, v23
	v_pk_mul_f32 v[16:17], v[16:17], v[24:25]
	v_rcp_f32_e32 v22, v22
	v_mul_f32_e32 v24, 0xbfb8aa3b, v12
	v_mul_f32_e32 v25, 0xbfb8aa3b, v13
	v_rcp_f32_e32 v23, v23
	v_exp_f32_e32 v24, v24
	v_exp_f32_e32 v25, v25
	v_pk_mul_f32 v[16:17], v[16:17], v[26:27] op_sel_hi:[1,0]
	v_pk_mul_f32 v[14:15], v[14:15], v[26:27] op_sel_hi:[1,0]
	v_pk_mul_f32 v[10:11], v[10:11], v[22:23]
	v_cvt_pk_bf16_f32 v14, v14, v15
	v_cvt_pk_bf16_f32 v15, v16, v17
	v_lshlrev_b32_e32 v16, 16, v40
	v_and_b32_e32 v17, 0xffff0000, v40
	v_add_f32_e32 v24, 1.0, v24
	v_add_f32_e32 v25, 1.0, v25
	v_pk_mul_f32 v[10:11], v[10:11], v[16:17]
	v_mul_f32_e32 v16, 0xbfb8aa3b, v6
	v_rcp_f32_e32 v24, v24
	v_rcp_f32_e32 v25, v25
	v_exp_f32_e32 v16, v16
	v_lshlrev_b32_e32 v22, 16, v41
	v_and_b32_e32 v23, 0xffff0000, v41
	v_pk_mul_f32 v[12:13], v[12:13], v[24:25]
	v_add_f32_e32 v16, 1.0, v16
	v_mul_f32_e32 v17, 0xbfb8aa3b, v8
	v_pk_mul_f32 v[12:13], v[12:13], v[22:23]
	v_rcp_f32_e32 v22, v16
	v_mul_f32_e32 v16, 0xbfb8aa3b, v7
	v_exp_f32_e32 v17, v17
	v_mul_f32_e32 v23, 0xbfb8aa3b, v9
	v_exp_f32_e32 v16, v16
	v_exp_f32_e32 v23, v23
	v_add_f32_e32 v17, 1.0, v17
	v_rcp_f32_e32 v24, v17
	v_add_f32_e32 v16, 1.0, v16
	v_add_f32_e32 v17, 1.0, v23
	v_rcp_f32_e32 v25, v17
	v_rcp_f32_e32 v23, v16
	v_pk_mul_f32 v[12:13], v[12:13], v[26:27] op_sel_hi:[1,0]
	v_pk_mul_f32 v[10:11], v[10:11], v[26:27] op_sel_hi:[1,0]
	v_cvt_pk_bf16_f32 v17, v12, v13
	v_cvt_pk_bf16_f32 v16, v10, v11
	v_pk_mul_f32 v[8:9], v[8:9], v[24:25]
	v_pk_mul_f32 v[6:7], v[6:7], v[22:23]
	v_lshlrev_b32_e32 v10, 16, v34
	v_and_b32_e32 v11, 0xffff0000, v34
	v_lshlrev_b32_e32 v12, 16, v35
	v_and_b32_e32 v13, 0xffff0000, v35
	v_pk_mul_f32 v[6:7], v[6:7], v[10:11]
	v_mul_f32_e32 v10, 0xbfb8aa3b, v2
	v_pk_mul_f32 v[8:9], v[8:9], v[12:13]
	v_mul_f32_e32 v11, 0xbfb8aa3b, v3
	v_mul_f32_e32 v12, 0xbfb8aa3b, v4
	v_mul_f32_e32 v13, 0xbfb8aa3b, v5
	v_exp_f32_e32 v10, v10
	v_exp_f32_e32 v11, v11
	v_exp_f32_e32 v12, v12
	v_exp_f32_e32 v13, v13
	v_add_f32_e32 v10, 1.0, v10
	v_add_f32_e32 v11, 1.0, v11
	v_add_f32_e32 v12, 1.0, v12
	v_add_f32_e32 v13, 1.0, v13
	v_rcp_f32_e32 v10, v10
	v_rcp_f32_e32 v12, v12
	v_rcp_f32_e32 v13, v13
	v_rcp_f32_e32 v11, v11
	v_pk_mul_f32 v[8:9], v[8:9], v[26:27] op_sel_hi:[1,0]
	v_pk_mul_f32 v[6:7], v[6:7], v[26:27] op_sel_hi:[1,0]
	v_pk_mul_f32 v[4:5], v[4:5], v[12:13]
	v_cvt_pk_bf16_f32 v6, v6, v7
	v_cvt_pk_bf16_f32 v7, v8, v9
	v_pk_mul_f32 v[2:3], v[2:3], v[10:11]
	v_lshlrev_b32_e32 v8, 16, v36
	v_and_b32_e32 v9, 0xffff0000, v36
	v_lshlrev_b32_e32 v10, 16, v37
	v_and_b32_e32 v11, 0xffff0000, v37
	v_pk_mul_f32 v[2:3], v[2:3], v[8:9]
	v_pk_mul_f32 v[4:5], v[4:5], v[10:11]
	v_pk_mul_f32 v[30:31], v[30:31], v[48:49] op_sel_hi:[1,0]
	v_pk_mul_f32 v[4:5], v[4:5], v[26:27] op_sel_hi:[1,0]
	v_pk_mul_f32 v[2:3], v[2:3], v[26:27] op_sel_hi:[1,0]
	v_cvt_pk_bf16_f32 v130, v30, v31
	v_cvt_pk_bf16_f32 v8, v2, v3
	v_cvt_pk_bf16_f32 v9, v4, v5
	global_store_dwordx4 v[42:43], v[6:9], off
	global_store_dwordx4 v[42:43], v[14:17], off offset:256
	global_store_dwordx4 v[152:153], v[18:21], off
	s_andn2_b64 vcc, exec, s[2:3]
	s_mov_b64 s[0:1], -1
	global_store_dwordx4 v[152:153], v[130:133], off offset:256
	s_cbranch_vccnz .LBB0_678
